# attention steady loop control flow straightened: step A falls through its wait/barrier into step B, step B inlines the loop-back barrier and loop-top scalars (5 taken branches per 2 steps -> 1)
# speedup vs baseline: 1.0221x; 1.0046x over previous
.LBB0_271:
	s_barrier
	s_add_i32 s44, s44, 0x10000
	s_cmp_ge_u32 s45, s94
	s_cbranch_scc1 .LBB0_283
	s_mov_b32 s96, s45
	s_branch .LBB0_261
.LBB0_277:
	s_waitcnt vmcnt(0) lgkmcnt(0)
	s_cbranch_execz .LBB0_265
	s_branch .LBB0_266
.LBB0_274:
	s_add_i32 s10, s44, 0xfffe8000
	s_and_b32 s10, s10, 0x10000
	s_add_i32 s10, s10, 0
	v_add_u32_e32 v237, s10, v222
	v_add_u32_e32 v80, v237, v223
	v_add_u32_e32 v236, s10, v233
	s_and_b32 s11, s44, 0x18000
	s_add_i32 s11, s93, s11
	ds_read_b128 v[96:99], v80 offset:32768
	ds_read_b128 v[184:187], v80 offset:40960
	v_add_u32_e32 v80, v237, v225
	ds_read_b128 v[180:183], v80 offset:32768
	ds_read_b128 v[176:179], v80 offset:40960
	v_add_u32_e32 v80, v236, v228
	ds_read_b128 v[172:175], v80 offset:16384
	ds_read_b128 v[168:171], v80 offset:20480
	ds_read_b128 v[164:167], v80 offset:24576
	ds_read_b128 v[160:163], v80 offset:28672
	v_mov_b32_e32 v80, v190
	s_nop 1
	v_permlane32_swap_b32_e32 v190, v80
	v_cmp_lt_f32_e32 vcc, s13, v190
	s_cbranch_vccz .LBB0_276
	v_max_f32_e32 v64, v190, v190
	v_max_f32_e32 v65, 0, v64
	v_exp_f32_e64 v80, -v65
	v_add_f32_e32 v229, v229, v65
	v_xor_b32_e32 v64, 0x80000000, v229
	v_sub_f32_e32 v127, v127, v65
	v_sub_f32_e32 v126, v126, v65
	v_sub_f32_e32 v125, v125, v65
	v_sub_f32_e32 v124, v124, v65
	v_sub_f32_e32 v123, v123, v65
	v_sub_f32_e32 v122, v122, v65
	v_sub_f32_e32 v121, v121, v65
	v_sub_f32_e32 v120, v120, v65
	v_sub_f32_e32 v119, v119, v65
	v_sub_f32_e32 v118, v118, v65
	v_sub_f32_e32 v117, v117, v65
	v_sub_f32_e32 v116, v116, v65
	v_sub_f32_e32 v115, v115, v65
	v_sub_f32_e32 v114, v114, v65
	v_sub_f32_e32 v113, v113, v65
	v_sub_f32_e32 v112, v112, v65
	v_sub_f32_e32 v143, v143, v65
	v_sub_f32_e32 v142, v142, v65
	v_sub_f32_e32 v141, v141, v65
	v_sub_f32_e32 v140, v140, v65
	v_sub_f32_e32 v139, v139, v65
	v_sub_f32_e32 v138, v138, v65
	v_sub_f32_e32 v137, v137, v65
	v_sub_f32_e32 v136, v136, v65
	v_sub_f32_e32 v135, v135, v65
	v_sub_f32_e32 v134, v134, v65
	v_sub_f32_e32 v133, v133, v65
	v_sub_f32_e32 v132, v132, v65
	v_sub_f32_e32 v131, v131, v65
	v_sub_f32_e32 v130, v130, v65
	v_sub_f32_e32 v129, v129, v65
	v_sub_f32_e32 v128, v128, v65
	v_mov_b32_e32 v65, v64
	v_mov_b32_e32 v66, v64
	v_mov_b32_e32 v67, v64
	v_mov_b32_e32 v68, v64
	v_mov_b32_e32 v69, v64
	v_mov_b32_e32 v70, v64
	v_mov_b32_e32 v71, v64
	v_mov_b32_e32 v72, v64
	v_mov_b32_e32 v73, v64
	v_mov_b32_e32 v74, v64
	v_mov_b32_e32 v75, v64
	v_mov_b32_e32 v76, v64
	v_mov_b32_e32 v77, v64
	v_mov_b32_e32 v78, v64
	v_mov_b32_e32 v79, v64
	v_pk_mul_f32 v[62:63], v[62:63], v[80:81] op_sel_hi:[1,0]
	v_pk_mul_f32 v[60:61], v[60:61], v[80:81] op_sel_hi:[1,0]
	v_pk_mul_f32 v[58:59], v[58:59], v[80:81] op_sel_hi:[1,0]
	v_pk_mul_f32 v[56:57], v[56:57], v[80:81] op_sel_hi:[1,0]
	v_pk_mul_f32 v[54:55], v[54:55], v[80:81] op_sel_hi:[1,0]
	v_pk_mul_f32 v[52:53], v[52:53], v[80:81] op_sel_hi:[1,0]
	v_pk_mul_f32 v[50:51], v[50:51], v[80:81] op_sel_hi:[1,0]
	v_pk_mul_f32 v[48:49], v[48:49], v[80:81] op_sel_hi:[1,0]
	v_pk_mul_f32 v[46:47], v[46:47], v[80:81] op_sel_hi:[1,0]
	v_pk_mul_f32 v[44:45], v[44:45], v[80:81] op_sel_hi:[1,0]
	v_pk_mul_f32 v[42:43], v[42:43], v[80:81] op_sel_hi:[1,0]
	v_pk_mul_f32 v[40:41], v[40:41], v[80:81] op_sel_hi:[1,0]
	v_pk_mul_f32 v[38:39], v[38:39], v[80:81] op_sel_hi:[1,0]
	v_pk_mul_f32 v[36:37], v[36:37], v[80:81] op_sel_hi:[1,0]
	v_pk_mul_f32 v[34:35], v[34:35], v[80:81] op_sel_hi:[1,0]
	v_pk_mul_f32 v[32:33], v[32:33], v[80:81] op_sel_hi:[1,0]
	v_pk_mul_f32 v[14:15], v[14:15], v[80:81] op_sel_hi:[1,0]
	v_pk_mul_f32 v[12:13], v[12:13], v[80:81] op_sel_hi:[1,0]
	v_pk_mul_f32 v[10:11], v[10:11], v[80:81] op_sel_hi:[1,0]
	v_pk_mul_f32 v[8:9], v[8:9], v[80:81] op_sel_hi:[1,0]
	v_pk_mul_f32 v[6:7], v[6:7], v[80:81] op_sel_hi:[1,0]
	v_pk_mul_f32 v[4:5], v[4:5], v[80:81] op_sel_hi:[1,0]
	v_pk_mul_f32 v[2:3], v[2:3], v[80:81] op_sel_hi:[1,0]
	v_pk_mul_f32 v[0:1], v[0:1], v[80:81] op_sel_hi:[1,0]
	v_pk_mul_f32 v[30:31], v[30:31], v[80:81] op_sel_hi:[1,0]
	v_pk_mul_f32 v[28:29], v[28:29], v[80:81] op_sel_hi:[1,0]
	v_pk_mul_f32 v[26:27], v[26:27], v[80:81] op_sel_hi:[1,0]
	v_pk_mul_f32 v[24:25], v[24:25], v[80:81] op_sel_hi:[1,0]
	v_pk_mul_f32 v[22:23], v[22:23], v[80:81] op_sel_hi:[1,0]
	v_pk_mul_f32 v[20:21], v[20:21], v[80:81] op_sel_hi:[1,0]
	v_pk_mul_f32 v[18:19], v[18:19], v[80:81] op_sel_hi:[1,0]
	v_pk_mul_f32 v[16:17], v[16:17], v[80:81] op_sel_hi:[1,0]
	v_pk_mul_f32 v[188:189], v[188:189], v[80:81] op_sel_hi:[1,0]

.Latt_dA3:
	v_mfma_f32_32x32x16_bf16 v[48:63], v[172:175], v[188:191], v[48:63]
	v_exp_f32_e32 v132, v132
	v_exp_f32_e32 v133, v133
	v_add_f32_e32 v172, v132, v237
	v_add_f32_e32 v173, v133, v219
	v_mfma_f32_32x32x16_bf16 v[32:47], v[168:171], v[188:191], v[32:47]
	v_exp_f32_e32 v134, v134
	v_exp_f32_e32 v135, v135
	v_add_f32_e32 v168, v134, v172
	v_add_f32_e32 v169, v135, v173
	v_mfma_f32_32x32x16_bf16 v[0:15], v[164:167], v[188:191], v[0:15]
	v_exp_f32_e32 v136, v136
	v_exp_f32_e32 v137, v137
	v_cvt_pk_bf16_f32 v164, v128, v129
	v_cvt_pk_bf16_f32 v165, v130, v131
	v_add_f32_e32 v166, v136, v168
	v_add_f32_e32 v167, v137, v169
	v_mfma_f32_32x32x16_bf16 v[16:31], v[160:163], v[188:191], v[16:31]
	v_exp_f32_e32 v138, v138
	v_exp_f32_e32 v139, v139
	v_add_f32_e32 v160, v138, v166
	v_add_f32_e32 v161, v139, v167
	v_cvt_pk_bf16_f32 v166, v132, v133
	v_cvt_pk_bf16_f32 v167, v134, v135
	v_exp_f32_e32 v140, v140
	v_exp_f32_e32 v141, v141
	s_waitcnt lgkmcnt(0)
	v_mfma_f32_32x32x16_bf16 v[48:63], v[238:241], v[176:179], v[48:63]
	v_add_u32_e32 v190, v236, v231
	v_add_f32_e32 v172, v140, v160
	v_add_f32_e32 v173, v141, v161
	ds_read_b128 v[160:163], v190 offset:16384
	ds_read_b128 v[168:171], v190 offset:20480
	v_exp_f32_e32 v142, v142
	v_exp_f32_e32 v143, v143
	v_mfma_f32_32x32x16_bf16 v[32:47], v[194:197], v[176:179], v[32:47]
	v_add_f32_e32 v189, v142, v172
	v_add_f32_e32 v188, v143, v173
	ds_read_b128 v[172:175], v190 offset:24576
	ds_read_b128 v[194:197], v190 offset:28672
	v_mfma_f32_32x32x16_bf16 v[0:15], v[184:187], v[176:179], v[0:15]
	v_cvt_pk_bf16_f32 v184, v136, v137
	v_cvt_pk_bf16_f32 v185, v138, v139
	v_mfma_f32_32x32x16_bf16 v[16:31], v[180:183], v[176:179], v[16:31]
	v_cvt_pk_bf16_f32 v186, v140, v141
	v_cvt_pk_bf16_f32 v187, v142, v143
	s_waitcnt lgkmcnt(0)
	v_mfma_f32_32x32x16_bf16 v[48:63], v[160:163], v[164:167], v[48:63]
	v_add_u32_e32 v180, v236, v232
	ds_read_b128 v[160:163], v180 offset:16384
	ds_read_b128 v[176:179], v180 offset:20480
	v_max_f32_e32 v181, v96, v96
	v_max_f32_e32 v182, v80, v80
	v_max_f32_e32 v190, v182, v181
	v_max3_f32 v191, v97, v82, v98
	v_mfma_f32_32x32x16_bf16 v[32:47], v[168:171], v[164:167], v[32:47]
	ds_read_b128 v[168:171], v180 offset:24576
	ds_read_b128 v[180:183], v180 offset:28672
	v_max3_f32 v190, v190, v81, v83
	v_max3_f32 v191, v191, v84, v100
	v_mfma_f32_32x32x16_bf16 v[0:15], v[172:175], v[164:167], v[0:15]
	v_max3_f32 v172, v190, v99, v85
	v_max3_f32 v173, v191, v86, v102
	v_mfma_f32_32x32x16_bf16 v[16:31], v[194:197], v[164:167], v[16:31]
	v_max3_f32 v164, v172, v101, v87
	v_max3_f32 v165, v173, v88, v104
	s_waitcnt lgkmcnt(0)
	v_mfma_f32_32x32x16_bf16 v[48:63], v[160:163], v[184:187], v[48:63]
	v_max3_f32 v160, v164, v103, v89
	v_max3_f32 v161, v165, v90, v106
	v_mfma_f32_32x32x16_bf16 v[32:47], v[176:179], v[184:187], v[32:47]
	v_max3_f32 v160, v160, v105, v91
	v_max3_f32 v161, v161, v92, v108
	v_mfma_f32_32x32x16_bf16 v[0:15], v[168:171], v[184:187], v[0:15]
	v_max3_f32 v160, v160, v107, v93
	v_max3_f32 v161, v161, v94, v110
	v_mfma_f32_32x32x16_bf16 v[16:31], v[180:183], v[184:187], v[16:31]
	v_max3_f32 v160, v160, v109, v95
	v_max3_f32 v190, v160, v111, v161
	s_mov_b64 s[80:81], -1
	s_and_b64 vcc, exec, s[38:39]
	s_cbranch_vccnz .LBB0_277
	s_waitcnt vmcnt(4) lgkmcnt(0)
	s_barrier
	s_add_i32 s10, s96, 6
	s_cmp_le_u32 s10, s94
	s_cselect_b64 s[38:39], -1, 0
	s_cmp_ge_u32 s45, s95
	s_cbranch_scc1 .LBB0_268

; __device__ __forceinline__ void attn_unit2(LAS unsigned char* lds, const bf16_t* Q, const bf16_t* K, const bf16_t* VT, bf16_t* Y, const float* subg, float lam, float outscale, int b, int h, int qb, int wid0) {
;     ...
;     for (int t = 0; t < nta; t += 2) {
;         A2_STEP(sA, sB, nA, nB, t);
;         A2_STEP(nA, nB, sA, sB, t + 1);
;     }
.LBB0_282:
	s_waitcnt vmcnt(4) lgkmcnt(0)
	s_cbranch_execz .LBB0_270
	s_barrier
	s_add_i32 s44, s44, 0x10000
	s_cmp_ge_u32 s45, s94
	s_cbranch_scc1 .LBB0_283
	s_mov_b32 s96, s45
	s_add_i32 s10, s96, 5
	s_cmp_ge_u32 s10, s22
	s_cselect_b64 s[38:39], -1, 0
	s_add_i32 s45, s96, 2
	s_cmp_gt_u32 s45, s95
	s_cbranch_scc0 .LBB0_274
	s_branch .LBB0_263
